# prologue de-serialisation of the attention phase: rpb table copy issues all loads before one wait instead of a load-wait-write loop
# baseline (speedup 1.0000x reference)
; #define LAS __attribute__((address_space(3)))
; __global__ void __launch_bounds__(512, 2) mega(Params P) {
;     ...
;                 LAS float* rpbL = (LAS float*)lds; int gw_o = (((int)blockIdx.x & 7) * 32 + ((int)blockIdx.x >> 3)) * 8 + wave; asm volatile("" : "+s"(gw_o));
;                 int tid_o = threadIdx.x; asm volatile("" : "+v"(tid_o)); const int lane_o = tid_o & 63;
;                 const float* rp = P.in[5] + (size_t)ly * 6 * 465;
;                 for (int i = tid_o; i < 6 * 465; i += 512) rpbL[i] = rp[i];
.LBB0_333:
	s_or_b64 exec, exec, s[34:35]
	v_readlane_b32 s4, v254, 16
	v_readlane_b32 s10, v254, 22
	v_readlane_b32 s18, v254, 30
	v_readlane_b32 s19, v254, 31
	s_mov_b64 s[42:43], s[18:19]
	v_readlane_b32 s10, v253, 22
	s_mov_b32 s81, s44
	v_readlane_b32 s1, v254, 42
	v_mov_b32_e32 v168, v238
	s_movk_i32 s2, 0xae6
	s_waitcnt lgkmcnt(0)
	s_barrier
	v_readlane_b32 s5, v254, 17
	v_cmp_gt_i32_e32 vcc, s2, v168
	v_readlane_b32 s6, v254, 18
	v_readlane_b32 s7, v254, 19
	v_readlane_b32 s8, v254, 20
	v_readlane_b32 s9, v254, 21
	v_readlane_b32 s11, v254, 23
	v_readlane_b32 s12, v254, 24
	v_readlane_b32 s13, v254, 25
	v_readlane_b32 s14, v254, 26
	v_readlane_b32 s15, v254, 27
	v_readlane_b32 s16, v254, 28
	v_readlane_b32 s17, v254, 29
	s_and_saveexec_b64 s[2:3], vcc
	s_cbranch_execz .LBB0_341
	v_readlane_b32 s6, v254, 10
	v_readlane_b32 s7, v254, 11
	s_mul_hi_i32 s11, s81, 0x2b98
	s_mul_i32 s12, s81, 0x2b98
	s_nop 1
	s_add_u32 s6, s6, s12
	s_addc_u32 s7, s7, s11
	v_lshlrev_b32_e32 v0, 2, v168
	global_load_dword v2, v0, s[6:7]
	global_load_dword v3, v0, s[6:7] offset:2048
	v_add_u32_e32 v8, 0x1000, v0
	global_load_dword v4, v8, s[6:7]
	global_load_dword v5, v8, s[6:7] offset:2048
	v_add_u32_e32 v9, 0x2000, v0
	global_load_dword v6, v9, s[6:7]
	v_add_u32_e32 v10, 0xa00, v168
	v_min_u32_e32 v11, 0xae5, v10
	v_lshlrev_b32_e32 v11, 2, v11
	global_load_dword v7, v11, s[6:7]
	s_waitcnt vmcnt(0)
	ds_write_b32 v0, v2
	ds_write_b32 v0, v3 offset:2048
	ds_write_b32 v0, v4 offset:4096
	ds_write_b32 v0, v5 offset:6144
	ds_write_b32 v0, v6 offset:8192
	v_cmp_gt_u32_e32 vcc, 0xae6, v10
	s_and_saveexec_b64 s[4:5], vcc
	ds_write_b32 v0, v7 offset:10240
	s_or_b64 exec, exec, s[4:5]
